# v31 with one s_nop restored in step B so the loop size change is a multiple of 8 bytes (placement check)
# speedup vs baseline: 1.0010x; 1.0010x over previous
.LBB0_971:
	s_add_u32 s36, s36, 0x180000
	s_addc_u32 s37, s37, 0
	s_add_i32 s25, s48, s77
	s_mov_b32 m0, s25
	s_nop 0
	global_load_lds_dwordx4 v228, s[36:37]
	s_add_i32 m0, s25, 0x400
	s_nop 0
	global_load_lds_dwordx4 v231, s[36:37]
	ds_read_b128 v[246:249], v243 offset:12288
	s_waitcnt lgkmcnt(3)
	v_mfma_f32_16x16x32_bf16 v[164:167], v[192:195], v[0:3], v[164:167]
	v_exp_f32_e32 v210, v132
	v_exp_f32_e32 v211, v133
	v_add_f32_e32 v212, v156, v245
	v_mfma_f32_16x16x32_bf16 v[160:163], v[192:195], v[36:39], v[160:163]
	v_add_f32_e32 v213, v148, v244
	v_add_u32_e32 v243, s49, v233
	ds_read_b128 v[192:195], v243
	v_exp_f32_e32 v250, v134
	v_exp_f32_e32 v251, v135
	s_waitcnt lgkmcnt(3)
	v_mfma_f32_16x16x32_bf16 v[132:135], v[188:191], v[0:3], v[180:183]
	v_add_f32_e32 v212, v157, v212
	v_add_f32_e32 v213, v149, v213
	v_mfma_f32_16x16x32_bf16 v[172:175], v[188:191], v[36:39], v[172:175]
	ds_read_b128 v[180:183], v243 offset:4096
	s_waitcnt lgkmcnt(3)
	v_mfma_f32_16x16x32_bf16 v[176:179], v[184:187], v[0:3], v[176:179]
	v_exp_f32_e32 v215, v128
	v_exp_f32_e32 v214, v129
	v_add_f32_e32 v188, v158, v212
	v_mfma_f32_16x16x32_bf16 v[140:143], v[184:187], v[36:39], v[140:143]
	v_add_f32_e32 v189, v150, v213
	ds_read_b128 v[184:187], v243 offset:8192
	v_exp_f32_e32 v218, v130
	v_exp_f32_e32 v198, v131
	s_waitcnt lgkmcnt(3)
	v_mfma_f32_16x16x32_bf16 v[128:131], v[246:249], v[0:3], v[168:171]
	v_add_f32_e32 v199, v159, v188
	v_add_f32_e32 v212, v151, v189
	v_mfma_f32_16x16x32_bf16 v[168:171], v[246:249], v[36:39], v[136:139]
	ds_read_b128 v[188:191], v243 offset:12288
	s_waitcnt lgkmcnt(3)
	v_mfma_f32_16x16x32_bf16 v[164:167], v[192:195], v[12:15], v[164:167]
	v_add_f32_e32 v137, v235, v199
	v_add_f32_e32 v138, v237, v212
	v_mfma_f32_16x16x32_bf16 v[160:163], v[192:195], v[28:31], v[160:163]
	v_cvt_pk_bf16_f32 v136, v152, v153
	v_add_u32_e32 v199, s49, v230
	ds_read_b128 v[192:195], v199
	v_add_f32_e32 v139, v236, v137
	v_add_f32_e32 v138, v238, v138
	s_waitcnt lgkmcnt(3)
	v_mfma_f32_16x16x32_bf16 v[132:135], v[180:183], v[12:15], v[132:135]
	v_cvt_pk_bf16_f32 v137, v154, v155
	v_mfma_f32_16x16x32_bf16 v[152:155], v[180:183], v[28:31], v[172:175]
	s_nop 2
	ds_read_b128 v[172:175], v199 offset:4096
	s_waitcnt lgkmcnt(3)
	v_mfma_f32_16x16x32_bf16 v[176:179], v[184:187], v[12:15], v[176:179]
	v_add_f32_e32 v139, v241, v139
	v_add_f32_e32 v212, v239, v138
	v_mfma_f32_16x16x32_bf16 v[140:143], v[184:187], v[28:31], v[140:143]
	v_cvt_pk_bf16_f32 v138, v156, v157
	ds_read_b128 v[180:183], v199 offset:8192
	v_add_f32_e32 v213, v242, v139
	v_add_f32_e32 v212, v240, v212
	s_waitcnt lgkmcnt(3)
	v_mfma_f32_16x16x32_bf16 v[128:131], v[188:191], v[12:15], v[128:131]
	v_cvt_pk_bf16_f32 v139, v158, v159
	v_mfma_f32_16x16x32_bf16 v[156:159], v[188:191], v[28:31], v[168:171]
	s_nop 2
	ds_read_b128 v[168:171], v199 offset:12288
	s_waitcnt lgkmcnt(3)
	v_mfma_f32_16x16x32_bf16 v[164:167], v[192:195], v[8:11], v[164:167]
	v_mfma_f32_16x16x32_bf16 v[184:187], v[192:195], v[24:27], v[160:163]
	s_nop 2
	v_add_f32_e32 v161, v210, v213
	v_add_f32_e32 v162, v215, v212
	v_cvt_pk_bf16_f32 v160, v144, v145
	v_add_u32_e32 v192, s49, v226
	ds_read_b128 v[188:191], v192 offset:16384
	v_add_f32_e32 v163, v211, v161
	v_add_f32_e32 v162, v214, v162
	s_waitcnt lgkmcnt(3)
	v_mfma_f32_16x16x32_bf16 v[132:135], v[172:175], v[8:11], v[132:135]
	v_cvt_pk_bf16_f32 v161, v146, v147
	v_mfma_f32_16x16x32_bf16 v[144:147], v[172:175], v[24:27], v[152:155]
	s_nop 2
	ds_read_b128 v[152:155], v192 offset:18432
	s_waitcnt lgkmcnt(3)
	v_mfma_f32_16x16x32_bf16 v[172:175], v[180:183], v[8:11], v[176:179]
	v_add_f32_e32 v163, v250, v163
	v_add_f32_e32 v193, v218, v162
	v_mfma_f32_16x16x32_bf16 v[140:143], v[180:183], v[24:27], v[140:143]
	v_cvt_pk_bf16_f32 v162, v148, v149
	ds_read_b128 v[176:179], v192 offset:20480
	v_add_f32_e32 v194, v251, v163
	v_add_f32_e32 v195, v198, v193
	s_waitcnt lgkmcnt(3)
	v_mfma_f32_16x16x32_bf16 v[128:131], v[168:171], v[8:11], v[128:131]
	v_cvt_pk_bf16_f32 v163, v150, v151
	v_mfma_f32_16x16x32_bf16 v[148:151], v[168:171], v[24:27], v[156:159]
	s_nop 2
	ds_read_b128 v[156:159], v192 offset:22528
	s_waitcnt lgkmcnt(3)
	v_mfma_f32_16x16x32_bf16 v[168:171], v[188:191], v[16:19], v[164:167]
	v_cvt_pk_bf16_f32 v164, v235, v236
	v_mfma_f32_16x16x32_bf16 v[180:183], v[188:191], v[32:35], v[184:187]
	v_add_u32_e32 v192, s49, v224
	s_nop 1
	ds_read_b128 v[184:187], v192 offset:16384
	s_waitcnt lgkmcnt(3)
	v_mfma_f32_16x16x32_bf16 v[132:135], v[152:155], v[16:19], v[132:135]
	v_cvt_pk_bf16_f32 v165, v241, v242
	v_mfma_f32_16x16x32_bf16 v[188:191], v[152:155], v[32:35], v[144:147]
	ds_read_b128 v[242:245], v192 offset:18432
	s_waitcnt lgkmcnt(3)
	v_mfma_f32_16x16x32_bf16 v[140:143], v[176:179], v[32:35], v[140:143]
	v_cvt_pk_bf16_f32 v166, v210, v211
	v_mfma_f32_16x16x32_bf16 v[246:249], v[176:179], v[16:19], v[172:175]
	ds_read_b128 v[176:179], v192 offset:20480
	s_waitcnt lgkmcnt(3)
	v_mfma_f32_16x16x32_bf16 v[128:131], v[156:159], v[16:19], v[128:131]
	v_cvt_pk_bf16_f32 v167, v250, v251
	v_mfma_f32_16x16x32_bf16 v[250:253], v[156:159], v[32:35], v[148:151]
	ds_read_b128 v[210:213], v192 offset:22528
	s_waitcnt lgkmcnt(3)
	v_mfma_f32_16x16x32_bf16 v[156:159], v[184:187], v[20:23], v[168:171]
	v_cvt_pk_bf16_f32 v168, v237, v238
	v_mfma_f32_16x16x32_bf16 v[144:147], v[184:187], v[44:47], v[180:183]
	s_waitcnt lgkmcnt(2)
	v_mfma_f32_16x16x32_bf16 v[152:155], v[242:245], v[20:23], v[132:135]
	v_cvt_pk_bf16_f32 v169, v239, v240
	v_mfma_f32_16x16x32_bf16 v[172:175], v[242:245], v[44:47], v[188:191]
	s_waitcnt lgkmcnt(1)
	v_mfma_f32_16x16x32_bf16 v[148:151], v[176:179], v[20:23], v[246:249]
	v_cvt_pk_bf16_f32 v170, v215, v214
	v_mfma_f32_16x16x32_bf16 v[140:143], v[176:179], v[44:47], v[140:143]
	s_waitcnt lgkmcnt(0)
	v_mfma_f32_16x16x32_bf16 v[132:135], v[210:213], v[20:23], v[128:131]
	v_cvt_pk_bf16_f32 v171, v218, v198
	v_mfma_f32_16x16x32_bf16 v[128:131], v[210:213], v[44:47], v[250:253]
	s_lshl_b32 s25, s5, 14
	s_add_i32 s25, s25, 0
	s_add_i32 s25, s25, 0x12000
	v_add_u32_e32 v235, s25, v222
	v_add_u32_e32 v236, s25, v223
	ds_read_b64_tr_b16 v[184:185], v236
	ds_read_b64_tr_b16 v[186:187], v236 offset:4096
	ds_read_b64_tr_b16 v[210:211], v236 offset:8192
	ds_read_b64_tr_b16 v[212:213], v236 offset:12288
	ds_read_b64_tr_b16 v[176:177], v235
	ds_read_b64_tr_b16 v[178:179], v235 offset:4096
	ds_read_b64_tr_b16 v[180:181], v235 offset:8192
	ds_read_b64_tr_b16 v[182:183], v235 offset:12288
	ds_read_b64_tr_b16 v[190:191], v236 offset:4608
	ds_read_b64_tr_b16 v[188:189], v236 offset:512
	ds_read_b64_tr_b16 v[240:241], v236 offset:12800
	ds_read_b64_tr_b16 v[238:239], v236 offset:8704
	s_waitcnt lgkmcnt(10)
	v_mfma_f32_16x16x32_bf16 v[112:115], v[184:187], v[136:139], v[112:115]
	v_mfma_f32_16x16x32_bf16 v[116:119], v[184:187], v[160:163], v[116:119]
	v_max_f32_e32 v184, v156, v157
	s_waitcnt lgkmcnt(8)
	v_mfma_f32_16x16x32_bf16 v[112:115], v[210:213], v[164:167], v[112:115]
	v_max3_f32 v184, v184, v158, v159
	v_max3_f32 v184, v184, v152, v153
	v_max3_f32 v184, v184, v154, v155
	v_mfma_f32_16x16x32_bf16 v[116:119], v[210:213], v[168:171], v[116:119]
	ds_read_b64_tr_b16 v[210:211], v235 offset:512
	ds_read_b64_tr_b16 v[212:213], v235 offset:4608
	ds_read_b64_tr_b16 v[242:243], v235 offset:8704
	ds_read_b64_tr_b16 v[244:245], v235 offset:12800
	s_waitcnt lgkmcnt(10)
	v_mfma_f32_16x16x32_bf16 v[104:107], v[176:179], v[136:139], v[104:107]
	v_mfma_f32_16x16x32_bf16 v[176:179], v[176:179], v[160:163], v[108:111]
	s_waitcnt lgkmcnt(8)
	v_mfma_f32_16x16x32_bf16 v[108:111], v[180:183], v[164:167], v[104:107]
	s_nop 5
	v_max3_f32 v104, v184, v148, v149
	v_max3_f32 v104, v104, v150, v151
	v_max3_f32 v104, v104, v132, v133
	v_max3_f32 v193, v104, v134, v135
	v_mfma_f32_16x16x32_bf16 v[104:107], v[180:183], v[168:171], v[176:179]
	ds_read_b64_tr_b16 v[184:185], v236 offset:1024
	ds_read_b64_tr_b16 v[186:187], v236 offset:5120
	s_nop 0
	ds_read_b64_tr_b16 v[176:177], v236 offset:9216
	ds_read_b64_tr_b16 v[178:179], v236 offset:13312
	s_waitcnt lgkmcnt(10)
	v_mfma_f32_16x16x32_bf16 v[96:99], v[188:191], v[136:139], v[96:99]
	v_max_f32_e32 v180, v144, v145
	s_waitcnt lgkmcnt(8)
	v_mfma_f32_16x16x32_bf16 v[96:99], v[238:241], v[164:167], v[96:99]
	v_max3_f32 v180, v180, v146, v147
	v_max3_f32 v180, v180, v172, v173
	v_max3_f32 v192, v180, v174, v175
	v_mfma_f32_16x16x32_bf16 v[100:103], v[188:191], v[160:163], v[100:103]
	v_mfma_f32_16x16x32_bf16 v[100:103], v[238:241], v[168:171], v[100:103]
	ds_read_b64_tr_b16 v[188:189], v235 offset:1024
	ds_read_b64_tr_b16 v[190:191], v235 offset:5120
	ds_read_b64_tr_b16 v[180:181], v235 offset:9216
	ds_read_b64_tr_b16 v[182:183], v235 offset:13312
	s_waitcnt lgkmcnt(10)
	v_mfma_f32_16x16x32_bf16 v[88:91], v[210:213], v[136:139], v[88:91]
	v_mfma_f32_16x16x32_bf16 v[210:213], v[210:213], v[160:163], v[92:95]
	s_waitcnt lgkmcnt(8)
	v_mfma_f32_16x16x32_bf16 v[92:95], v[242:245], v[164:167], v[88:91]
	s_nop 5
	v_max3_f32 v88, v192, v140, v141
	v_max3_f32 v88, v88, v142, v143
	v_max3_f32 v88, v88, v128, v129
	v_max3_f32 v237, v88, v130, v131
	v_max_f32_e32 v192, v193, v237
	v_cmp_ge_f32_e32 vcc, s62, v192
	v_mfma_f32_16x16x32_bf16 v[88:91], v[242:245], v[168:171], v[210:213]
	s_cmp_eq_u64 vcc, exec
	s_cselect_b64 s[36:37], 0, -1
	s_nop 0
	v_mov_b32_e32 v192, 1.0
	s_cbranch_scc1 .LBB0_973
	ds_bpermute_b32 v48, v220, v193
	v_max_f32_e32 v49, v193, v193
	v_max_f32_e32 v50, v237, v237
	s_waitcnt lgkmcnt(0)
	v_max_f32_e32 v48, v48, v48
	v_max_f32_e32 v48, v49, v48
	ds_bpermute_b32 v49, v221, v48
	s_waitcnt lgkmcnt(0)
	v_max3_f32 v48, v48, v49, 0
	ds_bpermute_b32 v49, v220, v237
	v_exp_f32_e64 v192, -v48
	v_sub_f32_e32 v156, v156, v48
	v_sub_f32_e32 v157, v157, v48
	v_sub_f32_e32 v158, v158, v48
	s_waitcnt lgkmcnt(0)
	v_max_f32_e32 v49, v49, v49
	v_max_f32_e32 v49, v50, v49
	ds_bpermute_b32 v50, v221, v49
	v_sub_f32_e32 v159, v159, v48
	v_sub_f32_e32 v152, v152, v48
	v_sub_f32_e32 v153, v153, v48
	v_sub_f32_e32 v154, v154, v48
	s_waitcnt lgkmcnt(0)
	v_max3_f32 v49, v49, v50, 0
	v_exp_f32_e64 v193, -v49
	v_pk_add_f32 v[202:203], v[202:203], v[48:49]
	v_sub_f32_e32 v155, v155, v48
	v_pk_add_f32 v[120:121], v[202:203], 0 neg_lo:[1,1] neg_hi:[1,1]
	v_xor_b32_e32 v124, 0x80000000, v203
	v_sub_f32_e32 v151, v151, v48
	v_sub_f32_e32 v150, v150, v48
	v_sub_f32_e32 v149, v149, v48
	v_sub_f32_e32 v148, v148, v48
	v_sub_f32_e32 v135, v135, v48
	v_sub_f32_e32 v134, v134, v48
	v_sub_f32_e32 v133, v133, v48
	v_sub_f32_e32 v132, v132, v48
	v_mov_b32_e32 v121, v120
	v_mov_b32_e32 v122, v120
	v_mov_b32_e32 v123, v120
	v_sub_f32_e32 v144, v144, v49
	v_sub_f32_e32 v145, v145, v49
	v_sub_f32_e32 v146, v146, v49
	v_sub_f32_e32 v147, v147, v49
	v_sub_f32_e32 v172, v172, v49
	v_sub_f32_e32 v173, v173, v49
	v_sub_f32_e32 v174, v174, v49
	v_sub_f32_e32 v175, v175, v49
	v_sub_f32_e32 v143, v143, v49
	v_sub_f32_e32 v142, v142, v49
	v_sub_f32_e32 v141, v141, v49
	v_sub_f32_e32 v140, v140, v49
	v_sub_f32_e32 v131, v131, v49
	v_sub_f32_e32 v130, v130, v49
	v_sub_f32_e32 v129, v129, v49
	v_sub_f32_e32 v128, v128, v49
	v_mov_b32_e32 v125, v124
	v_mov_b32_e32 v126, v124
	v_mov_b32_e32 v127, v124
	v_mov_b32_e32 v48, v120
	v_mov_b32_e32 v49, v120
	v_mov_b32_e32 v50, v120
	v_mov_b32_e32 v51, v120
	v_mov_b32_e32 v52, v124
	v_mov_b32_e32 v53, v124
	v_mov_b32_e32 v54, v124
	v_mov_b32_e32 v55, v124
	s_branch .LBB0_974
